# diff loop A-tile rescale test trimmed to v_cmp / s_or / one branch (was a 7-instruction, two-branch scalar chain); dead flag setup removed
# speedup vs baseline: 1.0208x; 1.0070x over previous
.LBB0_581:
	v_add_u32_e32 v161, s22, v218
	ds_read_b128 v[112:115], v161
	v_add_u32_e32 v160, s22, v217
	v_add_u32_e32 v222, s22, v216
	v_add_u32_e32 v221, s22, v215
	s_or_b32 s0, s23, s18
	s_cmp_eq_u32 s0, 0
	s_cselect_b64 s[14:15], -1, 0
	s_waitcnt lgkmcnt(0)
	v_mfma_f32_32x32x16_bf16 v[96:111], v[112:115], v[152:155], v[64:79]
	ds_read_b128 v[112:115], v160
	s_and_b64 s[2:3], exec, s[14:15]
	s_waitcnt lgkmcnt(0)
	v_mfma_f32_32x32x16_bf16 v[96:111], v[112:115], v[144:147], v[96:111]
	ds_read_b128 v[112:115], v222
	s_waitcnt lgkmcnt(0)
	v_mfma_f32_32x32x16_bf16 v[128:143], v[112:115], v[148:151], v[80:95]
	ds_read_b128 v[112:115], v221
	s_waitcnt lgkmcnt(0)
	v_mfma_f32_32x32x16_bf16 v[128:143], v[112:115], v[156:159], v[128:143]
	s_nop 5
	v_max3_f32 v112, v96, v97, v98
	v_max_f32_e32 v112, v112, v99
	v_max3_f32 v112, v112, v100, v101
	v_max3_f32 v112, v112, v102, v103
	v_max3_f32 v112, v112, v104, v105
	v_max3_f32 v112, v112, v106, v107
	v_max3_f32 v112, v112, v108, v109
	v_max3_f32 v112, v112, v110, v111
	v_cmp_nge_f32_e32 vcc, s85, v112
	s_or_b64 vcc, vcc, s[2:3]
	s_cbranch_vccz .LBB0_587
	v_and_b32_e32 v65, 64, v196
	v_xor_b32_e32 v64, 32, v196
	v_add_u32_e32 v65, 64, v65
	v_cmp_lt_i32_e32 vcc, v64, v65
	v_max_f32_e32 v65, v112, v112
	s_nop 0
	v_cndmask_b32_e32 v64, v196, v64, vcc
	v_lshlrev_b32_e32 v64, 2, v64
	ds_bpermute_b32 v64, v64, v112
	s_and_b64 vcc, exec, s[2:3]
	s_waitcnt lgkmcnt(0)
	v_max_f32_e32 v64, v64, v64
	v_max_f32_e32 v64, v65, v64
	v_max_f32_e32 v65, 0, v64
	s_cbranch_vccnz .LBB0_586
	v_exp_f32_e64 v66, -v65
	s_nop 0
	v_mul_f32_e32 v220, v220, v66
	v_pk_mul_f32 v[14:15], v[14:15], v[66:67] op_sel_hi:[1,0]
	v_pk_mul_f32 v[12:13], v[12:13], v[66:67] op_sel_hi:[1,0]
	v_pk_mul_f32 v[10:11], v[10:11], v[66:67] op_sel_hi:[1,0]
	v_pk_mul_f32 v[8:9], v[8:9], v[66:67] op_sel_hi:[1,0]
	v_pk_mul_f32 v[6:7], v[6:7], v[66:67] op_sel_hi:[1,0]
	v_pk_mul_f32 v[4:5], v[4:5], v[66:67] op_sel_hi:[1,0]
	v_pk_mul_f32 v[2:3], v[2:3], v[66:67] op_sel_hi:[1,0]
	v_pk_mul_f32 v[0:1], v[0:1], v[66:67] op_sel_hi:[1,0]
	v_pk_mul_f32 v[46:47], v[46:47], v[66:67] op_sel_hi:[1,0]
	v_pk_mul_f32 v[44:45], v[44:45], v[66:67] op_sel_hi:[1,0]
	v_pk_mul_f32 v[42:43], v[42:43], v[66:67] op_sel_hi:[1,0]
	v_pk_mul_f32 v[40:41], v[40:41], v[66:67] op_sel_hi:[1,0]
	v_pk_mul_f32 v[38:39], v[38:39], v[66:67] op_sel_hi:[1,0]
	v_pk_mul_f32 v[36:37], v[36:37], v[66:67] op_sel_hi:[1,0]
	v_pk_mul_f32 v[34:35], v[34:35], v[66:67] op_sel_hi:[1,0]
	v_pk_mul_f32 v[32:33], v[32:33], v[66:67] op_sel_hi:[1,0]

.LBB0_587:
.LBB0_588:
	ds_read_b128 v[162:165], v161 offset:4096
	s_and_b32 s0, s21, 0x100
	s_and_b32 s25, s21, 0x80
	v_bitop3_b32 v166, s25, v179, v207 bitop3:0xde
	s_add_i32 s24, s20, s0
	v_exp_f32_e32 v223, v96
	v_exp_f32_e32 v224, v97
	v_exp_f32_e32 v225, v98
	v_exp_f32_e32 v226, v99
	v_exp_f32_e32 v227, v100
	ds_read_b128 v[96:99], v160 offset:4096
	v_add_u32_e32 v100, s24, v166
	s_waitcnt lgkmcnt(0)
	v_mfma_f32_32x32x16_bf16 v[112:127], v[162:165], v[152:155], v[64:79]
	ds_read_b128 v[168:171], v100 offset:32768
	ds_read_b128 v[160:163], v100 offset:49152
	v_exp_f32_e32 v228, v101
	v_exp_f32_e32 v229, v102
	v_exp_f32_e32 v230, v103
	s_or_b32 s1, s25, 32
	v_bitop3_b32 v167, s1, v179, v207 bitop3:0xde
	v_exp_f32_e32 v231, v104
	v_add_u32_e32 v104, s24, v167
	v_mfma_f32_32x32x16_bf16 v[112:127], v[96:99], v[144:147], v[112:127]
	v_cvt_pk_bf16_f32 v96, v223, v224
	v_cvt_pk_bf16_f32 v97, v225, v226
	v_cvt_pk_bf16_f32 v98, v227, v228
	v_cvt_pk_bf16_f32 v99, v229, v230
	ds_read_b128 v[172:175], v104 offset:32768
	ds_read_b128 v[164:167], v104 offset:49152
	v_exp_f32_e32 v232, v105
	s_waitcnt lgkmcnt(0)
	v_mfma_f32_32x32x16_bf16 v[32:47], v[168:171], v[96:99], v[32:47]
	v_exp_f32_e32 v233, v106
	v_exp_f32_e32 v234, v107
	v_exp_f32_e32 v235, v108
	v_exp_f32_e32 v236, v109
	v_exp_f32_e32 v237, v110
	v_exp_f32_e32 v238, v111
	v_cvt_pk_bf16_f32 v100, v231, v232
	v_mfma_f32_32x32x16_bf16 v[0:15], v[160:163], v[96:99], v[0:15]
	v_cvt_pk_bf16_f32 v101, v233, v234
	v_cvt_pk_bf16_f32 v102, v235, v236
	v_cvt_pk_bf16_f32 v103, v237, v238
	v_max3_f32 v96, v128, v129, v130
	v_max_f32_e32 v96, v96, v131
	v_mfma_f32_32x32x16_bf16 v[32:47], v[172:175], v[100:103], v[32:47]
	v_max3_f32 v96, v96, v132, v133
	v_max3_f32 v96, v96, v134, v135
	v_max3_f32 v96, v96, v136, v137
	v_max3_f32 v96, v96, v138, v139
	v_max3_f32 v96, v96, v140, v141
	v_max3_f32 v96, v96, v142, v143
	v_mfma_f32_32x32x16_bf16 v[0:15], v[164:167], v[100:103], v[0:15]
	v_cmp_nge_f32_e32 vcc, s85, v96
	s_or_b64 vcc, vcc, s[2:3]
	s_cbranch_vccz .LBB0_594
	v_and_b32_e32 v81, 64, v196
	v_xor_b32_e32 v80, 32, v196
	v_add_u32_e32 v81, 64, v81
	v_cmp_lt_i32_e32 vcc, v80, v81
	v_max_f32_e32 v81, v96, v96
	s_nop 0
	v_cndmask_b32_e32 v80, v196, v80, vcc
	v_lshlrev_b32_e32 v80, 2, v80
	ds_bpermute_b32 v80, v80, v96
	s_and_b64 vcc, exec, s[2:3]
	s_waitcnt lgkmcnt(0)
	v_max_f32_e32 v80, v80, v80
	v_max_f32_e32 v80, v81, v80
	v_max_f32_e32 v81, 0, v80
	s_cbranch_vccnz .LBB0_593
	v_exp_f32_e64 v82, -v81
	s_nop 0
	v_mul_f32_e32 v219, v219, v82
	v_pk_mul_f32 v[62:63], v[62:63], v[82:83] op_sel_hi:[1,0]
	v_pk_mul_f32 v[60:61], v[60:61], v[82:83] op_sel_hi:[1,0]
	v_pk_mul_f32 v[58:59], v[58:59], v[82:83] op_sel_hi:[1,0]
	v_pk_mul_f32 v[56:57], v[56:57], v[82:83] op_sel_hi:[1,0]
	v_pk_mul_f32 v[54:55], v[54:55], v[82:83] op_sel_hi:[1,0]
	v_pk_mul_f32 v[52:53], v[52:53], v[82:83] op_sel_hi:[1,0]
	v_pk_mul_f32 v[50:51], v[50:51], v[82:83] op_sel_hi:[1,0]
	v_pk_mul_f32 v[48:49], v[48:49], v[82:83] op_sel_hi:[1,0]
	v_pk_mul_f32 v[30:31], v[30:31], v[82:83] op_sel_hi:[1,0]
	v_pk_mul_f32 v[28:29], v[28:29], v[82:83] op_sel_hi:[1,0]
	v_pk_mul_f32 v[26:27], v[26:27], v[82:83] op_sel_hi:[1,0]
	v_pk_mul_f32 v[24:25], v[24:25], v[82:83] op_sel_hi:[1,0]
	v_pk_mul_f32 v[22:23], v[22:23], v[82:83] op_sel_hi:[1,0]
	v_pk_mul_f32 v[20:21], v[20:21], v[82:83] op_sel_hi:[1,0]
	v_pk_mul_f32 v[18:19], v[18:19], v[82:83] op_sel_hi:[1,0]
	v_pk_mul_f32 v[16:17], v[16:17], v[82:83] op_sel_hi:[1,0]
